# drop the grid-wide barrier between G6 (first half) and G1 (second half): no data crosses it (G1 reads U/W_in, writes P/IF; G6 reads HID/x1, writes out); the workgroup barrier stays
# speedup vs baseline: 1.0089x; 1.0060x over previous
; __device__ __forceinline__ unsigned xb_add(unsigned* p, unsigned v) { return __hip_atomic_fetch_add(p, v, __ATOMIC_RELAXED, __HIP_MEMORY_SCOPE_AGENT); }
; #define GBAR() do { XcdBarrier xb_; xb_.bar = (unsigned*)(a.ws + WS_CTL) + 4096; xb_.x = xb_xcc_id(); xb_.st = (volatile LAS unsigned*)(lds + LDS_BYTES - 16); xcd_barrier(xb_); } while (0)
; __device__ __forceinline__ void xcd_barrier(const XcdBarrier& b) {
;     asm volatile("s_waitcnt vmcnt(0)" ::: "memory");
;     __syncthreads();
;     if (threadIdx.x == 0) {
;         unsigned* bar = b.bar;
;         __builtin_amdgcn_s_waitcnt(0);
;         unsigned nloc = b.st[0], nx = b.st[1];
;         if (nloc == 0u) { xcd_barrier_complete(bar, b.x, nloc, nx); b.st[0] = nloc; b.st[1] = nx; }
;         const unsigned old = xb_add(&bar[XB_XSUB(b.x)], 1u);
; __global__ void __launch_bounds__(512, 2) fwd_mega(Args a) {
;     ...
;           pg8::gemm_phase<EpiResid, pg8::StaticOrder, true, true>(lds, g, S, E); }
;         if (hb == 0) GBAR();
.LBB0_819:
	v_readlane_b32 s2, v254, 4
	v_readlane_b32 s3, v254, 5
	s_mov_b64 s[0:1], -1
	s_and_b64 vcc, exec, s[2:3]
	s_cbranch_vccz .LBB0_145
	s_getreg_b32 s2, hwreg(HW_REG_XCC_ID, 0, 4)
	s_waitcnt vmcnt(0)
	s_barrier
	s_mov_b64 s[0:1], exec
	s_branch .LBB0_144
	v_readlane_b32 s4, v251, 12
	v_readlane_b32 s5, v251, 13
	s_and_b64 s[4:5], s[0:1], s[4:5]
	s_mov_b64 exec, s[4:5]
	s_cbranch_execz .LBB0_144
	v_readlane_b32 s3, v253, 50
	s_waitcnt vmcnt(0) expcnt(0) lgkmcnt(0)
	s_and_b32 s8, s2, 15
	v_mov_b32_e32 v0, s3
	ds_read_b32 v3, v0
	v_readlane_b32 s3, v253, 51
	s_waitcnt lgkmcnt(0)
	v_cmp_ne_u32_e32 vcc, 0, v3
	v_mov_b32_e32 v0, s3
	ds_read_b32 v2, v0
	s_cbranch_vccnz .LBB0_836
	s_mov_b32 s9, 1
	s_branch .LBB0_824
